# norm2 phase: cross-item software pipelining (next item's row loads issued one iteration ahead)
# speedup vs baseline: 1.0012x; 1.0012x over previous
.LBB0_195:
	s_andn2_b64 vcc, exec, s[4:5]
	s_cbranch_vccnz .LBB0_200
	s_cmpk_gt_i32 s71, 0x7ff
	s_cbranch_scc1 .LBB0_200
	v_readlane_b32 s4, v254, 62
	s_lshl_b32 s94, s4, 13
	s_lshl_b32 s4, s22, 10
	s_ashr_i32 s5, s4, 31
	s_lshl_b64 s[4:5], s[4:5], 2
	v_readlane_b32 s52, v253, 8
	v_readlane_b32 s53, v253, 9
	v_readlane_b32 s54, v253, 10
	v_readlane_b32 s55, v253, 11
	v_readlane_b32 s56, v253, 12
	v_readlane_b32 s57, v253, 13
	v_readlane_b32 s58, v253, 14
	v_readlane_b32 s59, v253, 15
	v_readlane_b32 s60, v253, 16
	v_readlane_b32 s61, v253, 17
	v_readlane_b32 s62, v253, 18
	v_readlane_b32 s63, v253, 19
	v_readlane_b32 s64, v253, 20
	v_readlane_b32 s65, v253, 21
	v_readlane_b32 s66, v253, 22
	v_readlane_b32 s67, v253, 23
	s_add_u32 s4, s52, s4
	s_addc_u32 s5, s53, s5
	v_readlane_b32 s52, v252, 4
	s_lshl_b32 s20, s71, 2
	s_mov_b32 s21, s71
	v_readlane_b32 s24, v254, 38
	s_movk_i32 s25, 0x6000
	v_readlane_b32 s64, v252, 16
	v_readlane_b32 s65, v252, 17
	v_readlane_b32 s66, v252, 18
	v_readlane_b32 s67, v252, 19
	v_readlane_b32 s53, v252, 5
	v_readlane_b32 s54, v252, 6
	v_readlane_b32 s55, v252, 7
	v_readlane_b32 s56, v252, 8
	v_readlane_b32 s57, v252, 9
	v_readlane_b32 s58, v252, 10
	v_readlane_b32 s59, v252, 11
	v_readlane_b32 s60, v252, 12
	v_readlane_b32 s61, v252, 13
	v_readlane_b32 s62, v252, 14
	v_readlane_b32 s63, v252, 15
	s_mov_b32 m0, 1
.LBB0_198:
	v_mov_b32_e32 v0, v1
	v_readlane_b32 s22, v255, 2
	v_mbcnt_lo_u32_b32 v0, -1, v0
	v_mbcnt_hi_u32_b32 v0, -1, v0
	v_add_u32_e32 v0, s80, v0
	s_mul_i32 s22, s22, 3
	s_waitcnt lgkmcnt(0)
	v_ashrrev_i32_e32 v2, 6, v0
	v_add_u32_e32 v2, s20, v2
	v_ashrrev_i32_e32 v3, 31, v2
	v_lshl_add_u64 v[4:5], v[2:3], 0, s[94:95]
	v_ashrrev_i32_e32 v6, 12, v2
	v_lshlrev_b32_e32 v0, 2, v0
	v_lshlrev_b64 v[4:5], 12, v[4:5]
	v_add_u32_e32 v6, 1, v6
	v_and_b32_e32 v24, 0xfc, v0
	v_lshl_add_u64 v[4:5], s[64:65], 0, v[4:5]
	v_cndmask_b32_e64 v6, v6, 0, s[12:13]
	v_lshlrev_b32_e32 v0, 2, v24
	v_readlane_b32 s23, v255, 3
	v_add_u32_e32 v6, s22, v6
	v_lshl_add_u64 v[18:19], v[4:5], 0, v[0:1]
	v_mov_b64_e32 v[4:5], s[66:67]
	v_cmp_lt_i32_e32 vcc, v199, v221
	v_mad_i64_i32 v[4:5], s[22:23], v6, s25, v[4:5]
	s_nop 0
	v_cndmask_b32_e32 v6, v220, v199, vcc
	v_cmp_lt_i32_e32 vcc, v200, v221
	v_lshlrev_b32_e32 v54, 2, v6
	s_mov_b64 s[22:23], 0x4b03000
	v_cndmask_b32_e32 v6, v220, v200, vcc
	v_cmp_lt_i32_e32 vcc, v201, v221
	v_lshlrev_b32_e32 v55, 2, v6
	v_lshl_add_u64 v[20:21], v[4:5], 0, s[22:23]
	v_cndmask_b32_e32 v6, v220, v201, vcc
	v_cmp_lt_i32_e32 vcc, v235, v221
	v_lshlrev_b32_e32 v56, 2, v6
	s_mov_b64 s[22:23], 0x4b04000
	v_cndmask_b32_e32 v6, v220, v235, vcc
	v_cmp_lt_i32_e32 vcc, v226, v221
	v_lshlrev_b32_e32 v57, 2, v6
	v_lshlrev_b64 v[2:3], 11, v[2:3]
	v_cndmask_b32_e32 v6, v220, v226, vcc
	v_cmp_lt_i32_e32 vcc, v227, v221
	v_lshl_add_u64 v[38:39], v[4:5], 0, s[22:23]
	v_lshlrev_b32_e32 v58, 2, v6
	v_cndmask_b32_e32 v6, v220, v227, vcc
	v_lshl_add_u64 v[22:23], s[72:73], 0, v[2:3]
	v_lshl_add_u64 v[2:3], v[20:21], 0, v[0:1]
	v_lshl_add_u64 v[14:15], v[38:39], 0, v[0:1]
	v_lshlrev_b32_e32 v59, 2, v6
	v_mov_b32_e32 v60, v2
	v_mov_b32_e32 v61, v3
	v_mov_b32_e32 v62, v14
	v_mov_b32_e32 v63, v15
	s_cmp_eq_u32 m0, 1
	s_cbranch_scc0 .Ln2_nf
	global_load_dwordx4 v[66:69], v[18:19], off
	global_load_dwordx4 v[70:73], v[18:19], off offset:1024
	global_load_dwordx4 v[74:77], v[18:19], off offset:2048
	global_load_dwordx4 v[78:81], v[18:19], off offset:3072
	s_mov_b32 m0, 0
	s_branch .Ln2_j
.Ln2_nf:
	s_waitcnt vmcnt(4)
	v_mov_b32_e32 v66, v132
	v_mov_b32_e32 v67, v133
	v_mov_b32_e32 v68, v134
	v_mov_b32_e32 v69, v135
	v_mov_b32_e32 v70, v136
	v_mov_b32_e32 v71, v137
	v_mov_b32_e32 v72, v138
	v_mov_b32_e32 v73, v139
	v_mov_b32_e32 v74, v140
	v_mov_b32_e32 v75, v141
	v_mov_b32_e32 v76, v142
	v_mov_b32_e32 v77, v143
	v_mov_b32_e32 v78, v144
	v_mov_b32_e32 v79, v145
	v_mov_b32_e32 v80, v146
	v_mov_b32_e32 v81, v147
.Ln2_j:
	global_load_dwordx4 v[82:85], v0, s[4:5]
	global_load_dwordx4 v[86:89], v0, s[4:5] offset:1024
	global_load_dwordx4 v[90:93], v0, s[4:5] offset:2048
	global_load_dwordx4 v[94:97], v0, s[4:5] offset:3072
	global_load_dwordx4 v[98:101], v[60:61], off
	global_load_dwordx4 v[102:105], v[60:61], off offset:1024
	global_load_dwordx4 v[106:109], v[60:61], off offset:2048
	global_load_dwordx4 v[110:113], v[60:61], off offset:3072
	global_load_dwordx4 v[114:117], v[62:63], off
	global_load_dwordx4 v[118:121], v[62:63], off offset:1024
	global_load_dwordx4 v[122:125], v[62:63], off offset:2048
	global_load_dwordx4 v[126:129], v[62:63], off offset:3072
	v_lshlrev_b32_e32 v14, 1, v24
	v_mov_b32_e32 v15, v1
	v_lshl_add_u64 v[26:27], v[22:23], 0, v[14:15]
	s_add_i32 s21, s21, s81
	s_add_i32 s20, s20, s24
	v_readlane_b32 s22, v255, 2
	v_readlane_b32 s23, v255, 3
	s_cmpk_gt_i32 s21, 0x7ff
	s_cselect_b32 s98, 0, 0x800000
	s_mov_b32 s99, 0
	v_lshl_add_u64 v[64:65], v[18:19], 0, s[98:99]
	global_load_dwordx4 v[132:135], v[64:65], off
	global_load_dwordx4 v[136:139], v[64:65], off offset:1024
	global_load_dwordx4 v[140:143], v[64:65], off offset:2048
	global_load_dwordx4 v[144:147], v[64:65], off offset:3072
	s_waitcnt vmcnt(16)
	v_pk_mul_f32 v[130:131], v[66:67], v[66:67]
	v_pk_fma_f32 v[130:131], v[68:69], v[68:69], v[130:131]
	v_pk_fma_f32 v[130:131], v[70:71], v[70:71], v[130:131]
	v_pk_fma_f32 v[130:131], v[72:73], v[72:73], v[130:131]
	v_pk_fma_f32 v[130:131], v[74:75], v[74:75], v[130:131]
	v_pk_fma_f32 v[130:131], v[76:77], v[76:77], v[130:131]
	v_pk_fma_f32 v[130:131], v[78:79], v[78:79], v[130:131]
	v_pk_fma_f32 v[130:131], v[80:81], v[80:81], v[130:131]
	s_nop 0
	v_add_f32_e32 v44, v130, v131
	ds_bpermute_b32 v45, v54, v44
	s_waitcnt lgkmcnt(0)
	v_add_f32_e32 v44, v44, v45
	ds_bpermute_b32 v45, v55, v44
	s_waitcnt lgkmcnt(0)
	v_add_f32_e32 v44, v44, v45
	ds_bpermute_b32 v45, v56, v44
	s_waitcnt lgkmcnt(0)
	v_add_f32_e32 v44, v44, v45
	ds_bpermute_b32 v45, v57, v44
	s_waitcnt lgkmcnt(0)
	v_add_f32_e32 v44, v44, v45
	ds_bpermute_b32 v45, v58, v44
	s_waitcnt lgkmcnt(0)
	v_add_f32_e32 v44, v44, v45
	ds_bpermute_b32 v45, v59, v44
	s_waitcnt lgkmcnt(0)
	v_add_f32_e32 v44, v44, v45
	v_fmamk_f32 v44, v44, 0x3a800000, v187
	v_cmp_gt_f32_e32 vcc, s82, v44
	v_mul_f32_e32 v45, 0x4b800000, v44
	s_nop 0
	v_cndmask_b32_e32 v44, v44, v45, vcc
	v_rsq_f32_e32 v44, v44
	s_nop 0
	v_mul_f32_e32 v45, 0x45800000, v44
	v_cndmask_b32_e32 v44, v44, v45, vcc
	s_waitcnt vmcnt(4)
	v_pk_mul_f32 v[66:67], v[66:67], v[44:45] op_sel_hi:[1,0]
	v_pk_mul_f32 v[68:69], v[68:69], v[44:45] op_sel_hi:[1,0]
	v_pk_add_f32 v[114:115], v[114:115], 1.0 op_sel_hi:[1,0]
	v_pk_add_f32 v[116:117], v[116:117], 1.0 op_sel_hi:[1,0]
	v_pk_mul_f32 v[66:67], v[82:83], v[66:67]
	v_pk_mul_f32 v[68:69], v[84:85], v[68:69]
	v_pk_fma_f32 v[98:99], v[114:115], v[66:67], v[98:99]
	v_pk_fma_f32 v[100:101], v[68:69], v[116:117], v[100:101]
	s_nop 0
	v_cvt_pk_bf16_f32 v98, v98, v99
	v_cvt_pk_bf16_f32 v99, v100, v101
	global_store_dwordx2 v[26:27], v[98:99], off
	v_pk_mul_f32 v[70:71], v[70:71], v[44:45] op_sel_hi:[1,0]
	v_pk_mul_f32 v[72:73], v[72:73], v[44:45] op_sel_hi:[1,0]
	v_pk_add_f32 v[118:119], v[118:119], 1.0 op_sel_hi:[1,0]
	v_pk_add_f32 v[120:121], v[120:121], 1.0 op_sel_hi:[1,0]
	v_pk_mul_f32 v[70:71], v[86:87], v[70:71]
	v_pk_mul_f32 v[72:73], v[88:89], v[72:73]
	v_pk_fma_f32 v[102:103], v[118:119], v[70:71], v[102:103]
	v_pk_fma_f32 v[104:105], v[72:73], v[120:121], v[104:105]
	s_nop 0
	v_cvt_pk_bf16_f32 v102, v102, v103
	v_cvt_pk_bf16_f32 v103, v104, v105
	global_store_dwordx2 v[26:27], v[102:103], off offset:512
	v_pk_mul_f32 v[74:75], v[74:75], v[44:45] op_sel_hi:[1,0]
	v_pk_mul_f32 v[76:77], v[76:77], v[44:45] op_sel_hi:[1,0]
	v_pk_add_f32 v[122:123], v[122:123], 1.0 op_sel_hi:[1,0]
	v_pk_add_f32 v[124:125], v[124:125], 1.0 op_sel_hi:[1,0]
	v_pk_mul_f32 v[74:75], v[90:91], v[74:75]
	v_pk_mul_f32 v[76:77], v[92:93], v[76:77]
	v_pk_fma_f32 v[106:107], v[122:123], v[74:75], v[106:107]
	v_pk_fma_f32 v[108:109], v[76:77], v[124:125], v[108:109]
	s_nop 0
	v_cvt_pk_bf16_f32 v106, v106, v107
	v_cvt_pk_bf16_f32 v107, v108, v109
	global_store_dwordx2 v[26:27], v[106:107], off offset:1024
	v_pk_mul_f32 v[78:79], v[78:79], v[44:45] op_sel_hi:[1,0]
	v_pk_mul_f32 v[80:81], v[80:81], v[44:45] op_sel_hi:[1,0]
	v_pk_add_f32 v[126:127], v[126:127], 1.0 op_sel_hi:[1,0]
	v_pk_add_f32 v[128:129], v[128:129], 1.0 op_sel_hi:[1,0]
	v_pk_mul_f32 v[78:79], v[94:95], v[78:79]
	v_pk_mul_f32 v[80:81], v[96:97], v[80:81]
	v_pk_fma_f32 v[110:111], v[126:127], v[78:79], v[110:111]
	v_pk_fma_f32 v[112:113], v[80:81], v[128:129], v[112:113]
	s_nop 0
	v_cvt_pk_bf16_f32 v110, v110, v111
	v_cvt_pk_bf16_f32 v111, v112, v113
	global_store_dwordx2 v[26:27], v[110:111], off offset:1536
	s_cbranch_scc0 .LBB0_198
	s_mov_b32 s76, 0x8000
	s_mov_b32 s75, 0x60000
